# same as previous best but flipped block index computed as gridDim-1-blockIdx (grid-size robust)
# baseline (speedup 1.0000x reference)
_Z10fwd_kernel4Args:
	s_mov_b32 s99, 0
	s_load_dwordx8 s[20:27], s[0:1], 0xc0
	s_load_dword s33, s[0:1], 0xe0
	v_and_b32_e32 v1, 0x3ff, v0
	s_add_u32 s6, s0, 0xd8
	v_readfirstlane_b32 s10, v1
	v_mbcnt_lo_u32_b32 v2, -1, 0
	s_addc_u32 s7, s1, 0
	v_mbcnt_hi_u32_b32 v152, -1, v2
	s_and_b32 s3, s10, 0xffffffc0
	v_add_u32_e32 v153, s3, v152
	v_cmp_gt_i32_e32 vcc, 2, v153
	s_and_saveexec_b64 s[4:5], vcc
	v_lshl_add_u32 v2, v153, 2, 0
	v_add_u32_e32 v2, 0x20040, v2
	v_mov_b32_e32 v3, 0
	ds_write_b32 v2, v3
	s_or_b64 exec, exec, s[4:5]
	s_waitcnt lgkmcnt(0)
	s_sub_u32 s101, s26, 1
	s_sub_u32 s101, s101, s2
	s_barrier
	s_getreg_b32 s3, hwreg(HW_REG_XCC_ID, 0, 4)
	s_and_b32 s96, s3, 15
	v_cmp_eq_u32_e64 s[4:5], 0, v152
	s_cmp_lt_u32 s10, 64
	s_cselect_b64 s[8:9], -1, 0
	v_writelane_b32 v254, s4, 0
	s_nop 1
	v_writelane_b32 v254, s5, 1
	v_writelane_b32 v254, s8, 2
	s_and_b64 s[92:93], s[8:9], s[4:5]
	s_nop 0
	v_writelane_b32 v254, s9, 3
	s_and_saveexec_b64 s[4:5], s[92:93]
	s_cbranch_execz .LBB0_5
	s_mov_b64 s[12:13], exec
	v_mbcnt_lo_u32_b32 v2, s12, 0
	v_mbcnt_hi_u32_b32 v2, s13, v2
	v_cmp_eq_u32_e32 vcc, 0, v2
	s_and_b64 s[8:9], exec, vcc
	s_mov_b64 exec, s[8:9]
	s_cbranch_execz .LBB0_5
	s_lshl_b32 s3, s96, 8
	s_bcnt1_i32_b64 s8, s[12:13]
	v_mov_b32_e32 v2, s3
	v_mov_b32_e32 v3, s8
	global_atomic_add v2, v3, s[24:25] offset:1024
